# comb17 + gMLP and conv unit order grouped by XCD (the four quarters of a chunk / adjacent conv units share an L2)
# speedup vs baseline: 1.0101x; 1.0101x over previous
; #define LAS __attribute__((address_space(3)))
; #define KIN(i) (*(const float* const __attribute__((address_space(4)))*)(kp + kz + 8 * (i)))
; __global__ void __launch_bounds__(NTHR, 2) fwd_megakernel(Args args) {
;     ...
;         for (int su = bid; su < T / 32; su += G) {
;             const int tc0 = (su >> 2) * 128, qi = su & 3, i0 = 32 * qi, J = qi < 2 ? 64 : 128;
;             constexpr int LDB = 136;
;             LAS bf16_t* Bt = (LAS bf16_t*)lds;
;             LAS f32x2* st = (LAS f32x2*)(lds + 2 * 128 * LDB * 2);
;             LAS float* red = (LAS float*)(lds + 2 * 128 * LDB * 2 + 1024);
;             if (tid < J) { const f32x4* p = (const f32x4*)(VSTAT + (size_t)(tc0 + tid) * 32); float s1 = 0.f, s2 = 0.f;
; #pragma unroll
;                 for (int j = 0; j < 8; ++j) { const f32x4 v = p[j]; s1 += v[0] + v[2]; s2 += v[1] + v[3]; }
;                 const float mean = s1 * (1.0f / CCH), var = fmaxf(s2 * (1.0f / CCH) - mean * mean, 0.f); st[tid] = (f32x2){mean, rsqrtf(var + LN_EPS)}; }
;             const int mb = wave & 1, nq = wave >> 1, fr = lane & 15, fq = lane >> 4;
;             const int trow = tc0 + i0 + 16 * mb + fr;
;             const float* lng = KIN(I_SGU_LN_G); const float* lnb = KIN(I_SGU_LN_B); const float* sgb = KIN(I_SGU_B);
;             const int c8 = tid & 15, jb = tid >> 4, nk = J / 32;
;             u32x4 pv[4]; f32x4 pg0, pg1, pb0, pb1; bf16x8 pw[4]; u32x2 pu0, pu1; float pbs;
.LBB0_657:
	v_readlane_b32 s2, v254, 3
	s_add_i32 s11, 0, 0x11000
	s_bfe_u32 s4, s2, 0x10006
	s_lshr_b32 s5, s2, 7
	v_and_b32_e32 v2, 15, v221
	s_add_u32 s2, s0, s42
	v_mov_b32_e32 v121, 0
	v_lshl_or_b32 v155, s4, 4, v2
	s_addc_u32 s3, s1, s43
	v_and_b32_e32 v0, 48, v220
	v_mov_b32_e32 v1, v121
	s_lshl_b32 s4, s4, 8
	s_load_dwordx4 s[24:27], s[2:3], 0x58
	s_load_dwordx2 s[20:21], s[2:3], 0x70
	s_load_dwordx2 s[100:101], s[2:3], 0x80
	v_lshl_add_u64 v[0:1], s[14:15], 0, v[0:1]
	s_mov_b64 s[2:3], 0xbc00000
	s_add_i32 s4, s4, 0
	v_lshl_add_u64 v[128:129], v[0:1], 0, s[2:3]
	s_lshl_b32 s18, s5, 5
	v_mov_b32_e32 v0, 0x68
	s_add_i32 s4, s4, 0x11400
	s_lshl_b32 s5, s5, 6
	v_lshlrev_b32_e32 v120, 4, v2
	v_bitop3_b32 v7, s18, v0, v2 bitop3:0xc8
	s_add_i32 s23, s4, s5
	v_lshlrev_b32_e32 v0, 2, v2
	v_lshrrev_b32_e32 v3, 4, v220
	v_lshl_add_u64 v[122:123], s[36:37], 0, v[120:121]
	v_lshlrev_b32_e32 v120, 5, v2
	v_add_u32_e32 v175, s4, v0
	s_add_u32 s4, s88, s5
	s_waitcnt lgkmcnt(0)
	v_lshl_add_u64 v[124:125], s[24:25], 0, v[120:121]
	v_lshl_add_u64 v[126:127], s[26:27], 0, v[120:121]
	v_lshlrev_b32_e32 v120, 3, v3
	s_addc_u32 s5, s89, 0
	v_lshrrev_b32_e32 v163, 4, v221
	v_lshlrev_b32_e32 v4, 3, v2
	v_lshl_add_u64 v[130:131], s[4:5], 0, v[120:121]
	s_movk_i32 s4, 0x880
	v_or_b32_e32 v1, s18, v2
	v_add_u32_e32 v169, s23, v0
	v_lshl_or_b32 v0, v3, 2, s18
	v_mad_u32_u24 v2, v2, s4, 0
	v_xor_b32_e32 v3, v163, v4
	v_lshl_add_u32 v186, v3, 1, v2
	v_add_u32_e32 v3, 32, v163
	v_lshl_add_u32 v187, v3, 3, s11
	v_xor_b32_e32 v3, v3, v4
	v_lshl_add_u32 v188, v3, 1, v2
	v_or_b32_e32 v3, 64, v163
	v_lshl_add_u32 v189, v3, 3, s11
	v_bitop3_b32 v3, v163, v4, 64 bitop3:0x36
	s_movk_i32 s2, 0x110
	v_lshl_add_u32 v190, v3, 1, v2
	v_add_u32_e32 v3, 0x60, v163
	v_mul_lo_u32 v6, v1, s2
	s_movk_i32 s19, 0x68
	s_movk_i32 s22, 0x78
	v_lshl_add_u32 v191, v3, 3, s11
	v_xor_b32_e32 v3, v3, v4
	v_or_b32_e32 v5, 16, v1
	v_bitop3_b32 v8, v1, s22, 16 bitop3:0xc8
	v_lshl_add_u32 v192, v3, 1, v2
	v_add_u32_e32 v2, 0, v6
	v_bitop3_b32 v1, v120, v1, s19 bitop3:0x78
	v_add_u32_e32 v3, 0x1100, v2
	v_lshl_add_u32 v193, v1, 1, v2
	v_bitop3_b32 v1, v120, v5, s22 bitop3:0x78
	v_lshl_add_u32 v194, v1, 1, v3
	v_bitop3_b32 v1, v120, v7, 32 bitop3:0x36
	v_lshl_add_u32 v195, v1, 1, v2
	v_bitop3_b32 v1, v120, v8, 32 bitop3:0x36
	v_lshl_add_u32 v196, v1, 1, v3
	v_bitop3_b32 v1, v120, v7, 64 bitop3:0x36
	s_movk_i32 s4, 0x60
	v_lshl_add_u32 v197, v1, 1, v2
	v_bitop3_b32 v1, v120, v8, 64 bitop3:0x36
	v_lshl_add_u32 v198, v1, 1, v3
	v_bitop3_b32 v1, v120, v7, s4 bitop3:0x36
	v_lshl_add_u32 v199, v1, 1, v2
	v_bitop3_b32 v1, v120, v8, s4 bitop3:0x36
	v_lshlrev_b32_e32 v120, 1, v0
	v_lshl_add_u32 v137, v221, 3, s11
	v_cmp_gt_u32_e64 s[2:3], 16, v220
	v_lshl_add_u32 v181, v163, 3, s11
	v_lshl_add_u32 v200, v1, 1, v3
	v_lshl_add_u64 v[132:133], s[6:7], 0, v[120:121]
	s_lshl_b32 s23, s10, 5
	s_lshl_b32 s56, s34, 5
	s_mov_b32 s22, 0x3a800000
	s_mov_b32 s57, 0x800000
	v_and_b32_e32 v238, 0xff, v221
	v_lshlrev_b32_e32 v238, 4, v238
	v_mov_b32_e32 v239, 0
	v_lshl_add_u64 v[214:215], s[100:101], 0, v[238:239]
	v_cmp_gt_u32_e32 vcc, 0x100, v221
	v_mov_b32_e32 v240, s26
	v_mov_b32_e32 v241, s27
	v_mov_b32_e32 v242, s24
	v_mov_b32_e32 v243, s25
	s_nop 1
	v_cndmask_b32_e32 v240, v240, v242, vcc
	v_cndmask_b32_e32 v241, v241, v243, vcc
	v_lshl_add_u64 v[212:213], v[240:241], 0, v[238:239]
	v_lshl_add_u64 v[240:241], s[20:21], 0, v[238:239]
	v_cmp_gt_u32_e32 vcc, 0x100, v221
	s_nop 1
	v_cndmask_b32_e32 v214, v240, v214, vcc
	v_cndmask_b32_e32 v215, v241, v215, vcc
	v_lshrrev_b32_e32 v228, 4, v221
	v_mul_u32_u24_e32 v228, 0x110, v228
	v_and_b32_e32 v229, 15, v221
	v_lshl_add_u32 v228, v229, 4, v228
	v_add_u32_e32 v228, 0x15600, v228
	v_mul_u32_u24_e32 v229, 0x110, v155
	v_and_b32_e32 v240, 48, v220
	v_add3_u32 v229, v229, v240, 0
	v_add_u32_e32 v229, 0x15600, v229
	v_and_b32_e32 v203, 15, v221
	v_lshlrev_b32_e32 v203, 5, v203
	v_add_u32_e32 v203, 0x11600, v203
	s_mov_b64 s[24:25], 0x10000
	v_mov_b32_e32 v201, 0x358637bd
	v_lshlrev_b32_e32 v202, 2, v0
	s_nop 0
	s_lshr_b32 s4, s10, 5
	s_lshl_b32 s4, s4, 3
	s_and_b32 s5, s10, 7
	s_add_i32 s4, s4, s5
	s_lshl_b32 s4, s4, 2
	s_bfe_u32 s5, s10, 0x20003
	s_or_b32 s58, s4, s5
	s_lshl_b32 s23, s58, 5
	s_branch .LBB0_659
